# both split-phase fix-up barriers plus the dynamic per-XCD unit queue for the 4th+ units of the two gate/up GEMM phases
# speedup vs baseline: 1.0080x; 1.0020x over previous
.Ldq6_done:
	v_cmp_gt_i64_e32 vcc, s[24:25], v[150:151]
	v_cmp_lt_i64_e64 s[6:7], s[24:25], v[148:149]
	s_cbranch_vccnz .LBB0_733
	s_ashr_i32 s1, s24, 31
	s_lshr_b32 s1, s1, 29
	s_add_i32 s1, s24, s1
	s_ashr_i32 s2, s1, 3
	s_and_b32 s1, s1, -8
	s_sub_i32 s1, s24, s1
	s_cmp_lt_i32 s1, 0
	s_cselect_b32 s5, s41, 0xbb
	s_mul_i32 s1, s1, s5
	s_add_i32 s1, s1, s2
	s_cmp_lt_u32 s1, 0x580
	s_cbranch_scc1 .Ldw_skip
	s_cmp_eq_u32 s99, 1
	s_cbranch_scc1 .Ldw_skip
	s_mov_b32 s99, 1
	s_load_dwordx2 s[60:61], s[82:83], 0xb0
	s_getreg_b32 s94, hwreg(HW_REG_XCC_ID, 0, 4)
	s_and_b32 s94, s94, 15
	s_lshl_b32 s94, s94, 8
	s_add_i32 s94, s94, 0x2400
	v_mov_b32_e32 v231, s94
	s_mov_b32 s95, 0
	s_waitcnt lgkmcnt(0)
